# fft2 tile loads use the default cache policy instead of nt (on top of the merge task remap)
# baseline (speedup 1.0000x reference)
; template <bool RFA, bool RFB, class LA, class LB, class EPI>
; DI void gemm_tile2s(u16* smem, int nk, LA la, LB lb, EPI epi) {
;   const int tid = tidx(), lane = tid & 63, wave = tid >> 6;
;   const int wm = wave >> 2, wn = wave & 3, lr = lane & 31, lh = lane >> 5;
;   u16* As = smem;
;   u16* Bs = smem + 2 * TILE_ELEMS;
;   f32x16 acc[2];
;   acc[0] = zero16(); acc[1] = zero16();
;   u32x4 ra0[2], rb0[2], ra1[2], rb1[2];
;   auto ld = [&](u32x4 (&ra)[2], u32x4 (&rb)[2], int kt) __attribute__((always_inline)) {
;     const int k0 = kt * 64;
; #pragma unroll
;     for (int i = 0; i < 2; ++i) { const int c = tid + NTH * i; ra[i] = la(A_ROW(c), k0 + A_KC(c) * 8); rb[i] = lb(B_ROW(c), k0 + B_KC(c) * 8); }
;   };
;   auto stl = [&](u32x4 (&ra)[2], u32x4 (&rb)[2], int buf) __attribute__((always_inline)) {
; #pragma unroll
;     for (int i = 0; i < 2; ++i) {
;       const int c = tid + NTH * i;
;       *(u32x4*)(As + buf * TILE_ELEMS + A_ROW(c) * LDT + A_KC(c) * 8) = ra[i];
;       *(u32x4*)(Bs + buf * TILE_ELEMS + B_ROW(c) * LDT + B_KC(c) * 8) = rb[i];
;     }
;   };
;   auto compute = [&](int buf) __attribute__((always_inline)) {
;     const u16* Ab = As + buf * TILE_ELEMS + (wm * 64 + lr) * LDT + lh * 8;
;     const u16* Bb = Bs + buf * TILE_ELEMS + (wn * 32 + lr) * LDT + lh * 8;
; #pragma unroll
;     for (int ks = 0; ks < 4; ++ks) {
;       const bf16x8 a0 = *(const bf16x8*)(Ab + ks * 16);
;       const bf16x8 a1 = *(const bf16x8*)(Ab + 32 * LDT + ks * 16);
;       const bf16x8 b = *(const bf16x8*)(Bb + ks * 16);
;       acc[0] = mfma(a0, b, acc[0]);
;       acc[1] = mfma(a1, b, acc[1]);
;     }
;   };
;   ld(ra0, rb0, 0);
;   if (nk > 1) ld(ra1, rb1, 1);
;   stl(ra0, rb0, 0);
;   if (nk > 2) ld(ra0, rb0, 2);
; DI void phase_fft2(const Prm& p, u16* smem, int S, int nseq, int N1, int& base) {
;     ...
;   TASK_LOOP(t, ntask, base) {
;     const int ct = t % 6, k1 = (t / 6) % N1, seq = t / (6 * N1);
;     const u16* gb = p.Gp + ((size_t)((seq * N1 + k1) * 2) * 768 + ct * 128) * 128;
;     auto la = [&](int row, int k) __attribute__((always_inline)) {
;       const int part = k >> 7, s2 = k & 127, col = (row & ~31) + perm_m(row & 31);
;       return __builtin_nontemporal_load((const u32x4*)(gb + ((size_t)part * 768 + col) * 128 + s2));
;     };
;     auto lb = [&](int row, int k) __attribute__((always_inline)) { return *(const u32x4*)(p.M2 + row * 256 + k); };
.LBB0_2186:
	s_mul_hi_i32 s0, s6, 0x2aaaaaab
	s_lshr_b32 s1, s0, 31
	s_add_i32 s0, s0, s1
	s_mul_i32 s1, s0, 6
	s_ashr_i32 s2, s0, 31
	s_abs_i32 s0, s0
	v_readlane_b32 s3, v254, 56
	s_mul_hi_u32 s3, s0, s3
	s_mul_i32 s3, s3, s72
	s_sub_i32 s0, s0, s3
	s_sub_i32 s1, s6, s1
	s_sub_i32 s3, s0, s72
	s_cmp_ge_u32 s0, s72
	s_cselect_b32 s0, s3, s0
	s_sub_i32 s3, s0, s72
	s_cmp_ge_u32 s0, s72
	s_cselect_b32 s0, s3, s0
	s_xor_b32 s0, s0, s2
	s_sub_i32 s7, s0, s2
	s_abs_i32 s2, s6
	v_readlane_b32 s3, v254, 58
	s_mul_hi_u32 s3, s2, s3
	v_readlane_b32 s10, v254, 57
	s_mul_i32 s4, s3, s10
	s_sub_i32 s2, s2, s4
	s_ashr_i32 s0, s6, 31
	s_add_i32 s4, s3, 1
	s_sub_i32 s5, s2, s10
	s_cmp_ge_u32 s2, s10
	s_cselect_b32 s3, s4, s3
	s_cselect_b32 s2, s5, s2
	s_add_i32 s4, s3, 1
	s_cmp_ge_u32 s2, s10
	s_cselect_b32 s2, s4, s3
	s_xor_b32 s2, s2, s0
	s_sub_i32 s31, s2, s0
	s_lshl_b32 s0, s31, s52
	s_add_i32 s0, s0, s7
	v_mov_b32_e32 v26, v224
	s_lshl_b32 s2, s0, 1
	s_mul_i32 s3, s0, 0x600
	s_lshl_b32 s0, s1, 7
	s_ashr_i32 s1, s0, 31
	v_add_u32_e32 v10, 0x200, v26
	v_ashrrev_i32_e32 v27, 3, v26
	v_ashrrev_i32_e32 v28, 3, v10
	s_mul_hi_i32 s4, s2, 0x300
	s_add_u32 s2, s3, s0
	v_lshlrev_b32_e32 v0, 2, v27
	v_lshrrev_b32_e32 v2, 1, v27
	v_lshlrev_b32_e32 v10, 2, v28
	v_lshrrev_b32_e32 v11, 1, v28
	s_addc_u32 s3, s4, s1
	v_and_b32_e32 v0, 16, v0
	v_and_b32_e32 v2, 12, v2
	v_and_b32_e32 v3, 0xffffffe3, v27
	v_and_b32_e32 v10, 16, v10
	v_and_b32_e32 v11, 12, v11
	v_and_b32_e32 v12, 0xffffffe3, v28
	s_lshl_b64 s[2:3], s[2:3], 8
	v_readlane_b32 s36, v253, 24
	v_or3_b32 v2, v2, v3, v0
	v_lshlrev_b32_e32 v6, 8, v27
	v_or3_b32 v10, v11, v12, v10
	v_readlane_b32 s37, v253, 25
	s_add_u32 s2, s36, s2
	v_ashrrev_i32_e32 v3, 31, v2
	v_lshlrev_b32_e32 v0, 4, v26
	v_ashrrev_i32_e32 v7, 31, v6
	v_ashrrev_i32_e32 v11, 31, v10
	v_lshlrev_b32_e32 v14, 8, v28
	s_addc_u32 s3, s37, s3
	v_lshlrev_b64 v[2:3], 8, v[2:3]
	v_and_b32_e32 v0, 0x70, v0
	v_lshl_add_u64 v[6:7], v[6:7], 1, s[8:9]
	v_lshlrev_b64 v[10:11], 8, v[10:11]
	v_ashrrev_i32_e32 v15, 31, v14
	v_lshl_add_u64 v[18:19], s[2:3], 0, v[2:3]
	v_lshl_add_u64 v[66:67], v[6:7], 0, v[0:1]
	v_lshl_add_u64 v[22:23], s[2:3], 0, v[10:11]
	v_lshl_add_u64 v[14:15], v[14:15], 1, s[8:9]
	s_mov_b64 s[2:3], 0x30000
	v_lshl_add_u64 v[20:21], v[18:19], 0, v[0:1]
	global_load_dwordx4 v[6:9], v[66:67], off
	v_lshl_add_u64 v[24:25], v[22:23], 0, v[0:1]
	s_waitcnt vmcnt(2)
	v_lshl_add_u64 v[72:73], v[14:15], 0, v[0:1]
	v_lshl_add_u64 v[18:19], v[18:19], 0, s[2:3]
	v_lshl_add_u64 v[22:23], v[22:23], 0, s[2:3]
	global_load_dwordx4 v[2:5], v[20:21], off
	global_load_dwordx4 v[10:13], v[24:25], off
	global_load_dwordx4 v[14:17], v[72:73], off
	global_load_dwordx4 v[34:37], v[20:21], off offset:128
	global_load_dwordx4 v[42:45], v[66:67], off offset:128
	global_load_dwordx4 v[38:41], v[24:25], off offset:128
	v_lshl_add_u64 v[20:21], v[18:19], 0, v[0:1]
	global_load_dwordx4 v[46:49], v[66:67], off offset:256
	v_lshl_add_u64 v[24:25], v[22:23], 0, v[0:1]
	global_load_dwordx4 v[62:65], v[72:73], off offset:128
	global_load_dwordx4 v[50:53], v[72:73], off offset:256
	global_load_dwordx4 v[54:57], v[20:21], off
	global_load_dwordx4 v[58:61], v[24:25], off
	v_and_b32_e32 v20, 31, v26
	v_ashrrev_i32_e32 v21, 2, v26
	v_lshrrev_b32_e32 v24, 1, v26
	v_and_b32_e32 v68, 0xffffffc0, v21
	v_mad_u64_u32 v[74:75], s[2:3], v27, s70, v[0:1]
	v_and_or_b32 v69, v24, s86, v20
	v_and_b32_e32 v70, 16, v24
	s_waitcnt vmcnt(12)
	v_mad_u64_u32 v[76:77], s[2:3], v28, s70, v[0:1]
	v_or_b32_e32 v21, v68, v20
	v_mad_u64_u32 v[78:79], s[2:3], v21, s70, v[70:71]
	v_or_b32_e32 v0, 0x80, v0
	v_lshl_add_u64 v[80:81], v[18:19], 0, v[0:1]
	v_lshl_add_u64 v[82:83], v[22:23], 0, v[0:1]
	s_mov_b64 s[2:3], -1
	s_mov_b32 s8, s52
	v_readlane_b32 s38, v253, 26
	v_readlane_b32 s39, v253, 27
	s_waitcnt vmcnt(11)
	ds_write_b128 v74, v[6:9] offset:36864
	s_waitcnt vmcnt(10)
	ds_write_b128 v74, v[2:5]
	s_waitcnt vmcnt(9)
	ds_write_b128 v76, v[10:13]
	s_waitcnt vmcnt(8)
	ds_write_b128 v76, v[14:17] offset:36864
	v_mul_u32_u24_e32 v2, 0x48, v69
	v_lshl_add_u32 v71, v2, 1, v70
	v_mov_b32_e32 v2, 0
	v_mov_b32_e32 v3, v2
	v_mov_b32_e32 v4, v2
	v_mov_b32_e32 v5, v2
	v_mov_b32_e32 v6, v2
	v_mov_b32_e32 v7, v2
	v_mov_b32_e32 v8, v2
	v_mov_b32_e32 v9, v2
	v_mov_b32_e32 v10, v2
	v_mov_b32_e32 v11, v2
	v_mov_b32_e32 v12, v2
	v_mov_b32_e32 v13, v2
	v_mov_b32_e32 v14, v2
	v_mov_b32_e32 v15, v2
	v_mov_b32_e32 v16, v2
	v_mov_b32_e32 v17, v2
	v_mov_b32_e32 v18, v2
	v_mov_b32_e32 v19, v2
	v_mov_b32_e32 v20, v2
	v_mov_b32_e32 v21, v2
	v_mov_b32_e32 v22, v2
	v_mov_b32_e32 v23, v2
	v_mov_b32_e32 v24, v2
	v_mov_b32_e32 v25, v2
	v_mov_b32_e32 v26, v2
	v_mov_b32_e32 v27, v2
	v_mov_b32_e32 v28, v2
	v_mov_b32_e32 v29, v2
	v_mov_b32_e32 v30, v2
	v_mov_b32_e32 v31, v2
	v_mov_b32_e32 v32, v2
	v_mov_b32_e32 v33, v2
	v_readlane_b32 s40, v253, 28
	v_readlane_b32 s41, v253, 29
	v_readlane_b32 s42, v253, 30
	v_readlane_b32 s43, v253, 31
	v_readlane_b32 s44, v253, 32
	v_readlane_b32 s45, v253, 33
	v_readlane_b32 s46, v253, 34
	v_readlane_b32 s47, v253, 35
	v_readlane_b32 s48, v253, 36
	v_readlane_b32 s49, v253, 37
	v_readlane_b32 s50, v253, 38
	v_readlane_b32 s51, v253, 39
	s_waitcnt lgkmcnt(0)
	s_barrier
	s_branch .LBB0_2188

; DI f32x16 mfma(bf16x8 a, bf16x8 b, f32x16 c) { return __builtin_amdgcn_mfma_f32_32x32x16_bf16(a, b, c, 0, 0, 0); }
; template <bool RFA, bool RFB, class LA, class LB, class EPI>
; DI void gemm_tile2s(u16* smem, int nk, LA la, LB lb, EPI epi) {
;     ...
;   auto compute = [&](int buf) __attribute__((always_inline)) {
;     const u16* Ab = As + buf * TILE_ELEMS + (wm * 64 + lr) * LDT + lh * 8;
;     const u16* Bb = Bs + buf * TILE_ELEMS + (wn * 32 + lr) * LDT + lh * 8;
; #pragma unroll
;     for (int ks = 0; ks < 4; ++ks) {
;       const bf16x8 a0 = *(const bf16x8*)(Ab + ks * 16);
;       const bf16x8 a1 = *(const bf16x8*)(Ab + 32 * LDT + ks * 16);
;       const bf16x8 b = *(const bf16x8*)(Bb + ks * 16);
;       acc[0] = mfma(a0, b, acc[0]);
;       acc[1] = mfma(a1, b, acc[1]);
;     }
;   };
;   ld(ra0, rb0, 0);
;   if (nk > 1) ld(ra1, rb1, 1);
;   stl(ra0, rb0, 0);
;   if (nk > 2) ld(ra0, rb0, 2);
;   __syncthreads();
; #pragma unroll 1
;   for (int kt = 0; kt < nk; kt += 2) {
;     compute(0);
;     if (kt + 1 < nk) { stl(ra1, rb1, 1); if (kt + 3 < nk) ld(ra1, rb1, kt + 3); }
; DI void phase_fft2(const Prm& p, u16* smem, int S, int nseq, int N1, int& base) {
;     ...
;     auto la = [&](int row, int k) __attribute__((always_inline)) {
;       const int part = k >> 7, s2 = k & 127, col = (row & ~31) + perm_m(row & 31);
;       return __builtin_nontemporal_load((const u32x4*)(gb + ((size_t)part * 768 + col) * 128 + s2));
;     };
;     auto lb = [&](int row, int k) __attribute__((always_inline)) { return *(const u32x4*)(p.M2 + row * 256 + k); };
.LBB0_2188:
	ds_read_b128 v[84:87], v78
	ds_read_b128 v[88:91], v71 offset:36864
	s_xor_b64 s[4:5], s[2:3], -1
	s_and_b64 vcc, exec, s[4:5]
	s_waitcnt lgkmcnt(0)
	v_mfma_f32_32x32x16_bf16 v[18:33], v[84:87], v[88:91], v[18:33]
	ds_read_b128 v[84:87], v78 offset:4608
	s_waitcnt lgkmcnt(0)
	v_mfma_f32_32x32x16_bf16 v[2:17], v[84:87], v[88:91], v[2:17]
	ds_read_b128 v[84:87], v78 offset:32
	ds_read_b128 v[88:91], v71 offset:36896
	s_waitcnt lgkmcnt(0)
	v_mfma_f32_32x32x16_bf16 v[18:33], v[84:87], v[88:91], v[18:33]
	ds_read_b128 v[84:87], v78 offset:4640
	s_waitcnt lgkmcnt(0)
	v_mfma_f32_32x32x16_bf16 v[2:17], v[84:87], v[88:91], v[2:17]
	ds_read_b128 v[84:87], v78 offset:64
	ds_read_b128 v[88:91], v71 offset:36928
	s_waitcnt lgkmcnt(0)
	v_mfma_f32_32x32x16_bf16 v[18:33], v[84:87], v[88:91], v[18:33]
	ds_read_b128 v[84:87], v78 offset:4672
	s_waitcnt lgkmcnt(0)
	v_mfma_f32_32x32x16_bf16 v[2:17], v[84:87], v[88:91], v[2:17]
	ds_read_b128 v[84:87], v78 offset:96
	ds_read_b128 v[88:91], v71 offset:36960
	s_waitcnt lgkmcnt(0)
	v_mfma_f32_32x32x16_bf16 v[18:33], v[84:87], v[88:91], v[18:33]
	ds_read_b128 v[84:87], v78 offset:4704
	s_waitcnt vmcnt(3)
	ds_write_b128 v74, v[34:37] offset:18432
	s_waitcnt vmcnt(1)
	ds_write_b128 v74, v[42:45] offset:55296
	s_waitcnt vmcnt(5)
	ds_write_b128 v76, v[38:41] offset:18432
	s_waitcnt vmcnt(0)
	ds_write_b128 v76, v[62:65] offset:55296
	s_waitcnt lgkmcnt(4)
	v_mfma_f32_32x32x16_bf16 v[2:17], v[84:87], v[88:91], v[2:17]
	s_cbranch_vccnz .LBB0_2190
	global_load_dwordx4 v[34:37], v[80:81], off
	global_load_dwordx4 v[38:41], v[82:83], off
	global_load_dwordx4 v[42:45], v[66:67], off offset:384
	global_load_dwordx4 v[62:65], v[72:73], off offset:384
